# EpiOddGate epilogue: rs and HN loads of iterations 1..5 hoisted to the top, counted waits leave the stores in flight
# speedup vs baseline: 1.0122x; 1.0122x over previous
.LBB0_805:
	s_min_i32 s15, s33, 64
	v_lshl_add_u32 v162, s33, 8, v1
	s_lshr_b32 s15, s15, 4
	v_ashrrev_i32_e32 v163, 31, v162
	s_mul_i32 s22, s15, 0x1600
	v_lshl_add_u64 v[40:41], v[162:163], 2, s[4:5]
	s_ashr_i32 s23, s22, 31
	global_load_dword v166, v[40:41], off
	s_lshl_b64 s[22:23], s[22:23], 2
	v_lshl_or_b32 v38, s44, 8, v169
	s_add_u32 s22, s28, s22
	v_ashrrev_i32_e32 v39, 31, v38
	s_addc_u32 s23, s29, s23
	v_lshlrev_b64 v[164:165], 11, v[162:163]
	v_lshl_add_u64 v[54:55], v[38:39], 2, s[22:23]
	s_mov_b64 s[22:23], 0xf1000
	s_mov_b32 s15, 0xf1000
	v_lshl_add_u64 v[40:41], s[8:9], 0, v[164:165]
	v_lshlrev_b64 v[160:161], 1, v[38:39]
	v_add_u32_e32 v171, v164, v160
	v_lshlrev_b32_e32 v222, 2, v162
	v_lshl_add_u64 v[38:39], v[54:55], 0, s[22:23]
	v_add_co_u32_e32 v54, vcc, s15, v54
	v_lshl_add_u64 v[40:41], v[40:41], 0, v[160:161]
	s_nop 0
	v_addc_co_u32_e32 v55, vcc, 0, v55, vcc
	global_load_dwordx4 v[172:175], v[40:41], off
	global_load_dwordx4 v[176:179], v[40:41], off offset:256
	global_load_dwordx4 v[50:53], v[38:39], off offset:16
	global_load_dwordx4 v[46:49], v[38:39], off offset:512
	s_nop 0
	global_load_dwordx4 v[38:41], v[38:39], off offset:528
	v_lshl_add_u64 v[164:165], s[10:11], 0, v[164:165]
	global_load_dwordx4 v[54:57], v[54:55], off
	v_add_u32_e32 v245, 0x8000, v171
	global_load_dwordx4 v[190:193], v245, s[8:9]
	global_load_dwordx4 v[194:197], v245, s[8:9] offset:256
	global_load_dword v240, v222, s[4:5] offset:64
	v_add_u32_e32 v223, 0x10000, v171
	global_load_dwordx4 v[198:201], v223, s[8:9]
	global_load_dwordx4 v[202:205], v223, s[8:9] offset:256
	global_load_dword v241, v222, s[4:5] offset:128
	v_add_u32_e32 v245, 0x18000, v171
	global_load_dwordx4 v[206:209], v245, s[8:9]
	global_load_dwordx4 v[210:213], v245, s[8:9] offset:256
	global_load_dword v242, v222, s[4:5] offset:192
	v_add_u32_e32 v223, 0x40000, v171
	global_load_dwordx4 v[214:217], v223, s[8:9]
	global_load_dwordx4 v[218:221], v223, s[8:9] offset:256
	global_load_dword v243, v222, s[4:5] offset:512
	v_add_u32_e32 v245, 0x48000, v171
	global_load_dwordx4 v[226:229], v245, s[8:9]
	global_load_dwordx4 v[236:239], v245, s[8:9] offset:256
	global_load_dword v244, v222, s[4:5] offset:576
	v_lshl_add_u64 v[164:165], v[164:165], 0, v[160:161]
	s_andn2_b64 vcc, exec, s[6:7]
	s_mov_b64 s[6:7], -1
	s_waitcnt vmcnt(15)
	v_fmamk_f32 v163, v166, 0x3a800000, v225
	v_rsq_f32_e32 v166, v163
	v_lshlrev_b32_e32 v182, 16, v174
	v_pk_fma_f32 v[142:143], v[142:143], v[166:167], v[50:51] op_sel_hi:[1,0,1]
	v_pk_fma_f32 v[144:145], v[144:145], v[166:167], v[52:53] op_sel_hi:[1,0,1]
	v_pk_fma_f32 v[136:137], v[136:137], v[166:167], v[48:49] op_sel_hi:[1,0,1]
	v_pk_fma_f32 v[186:187], v[132:133], v[166:167], v[40:41] op_sel_hi:[1,0,1]
	v_pk_fma_f32 v[188:189], v[130:131], v[166:167], v[38:39] op_sel_hi:[1,0,1]
	v_mul_f32_e32 v142, 0xbfb8aa3b, v142
	v_mul_f32_e32 v143, 0xbfb8aa3b, v143
	v_pk_fma_f32 v[130:131], v[140:141], v[166:167], v[56:57] op_sel_hi:[1,0,1]
	v_pk_fma_f32 v[132:133], v[138:139], v[166:167], v[54:55] op_sel_hi:[1,0,1]
	v_mul_f32_e32 v144, 0xbfb8aa3b, v144
	v_mul_f32_e32 v145, 0xbfb8aa3b, v145
	v_mul_f32_e32 v136, 0xbfb8aa3b, v136
	v_mul_f32_e32 v163, 0xbfb8aa3b, v137
	v_exp_f32_e32 v137, v142
	v_exp_f32_e32 v138, v143
	v_mul_f32_e32 v132, 0xbfb8aa3b, v132
	v_mul_f32_e32 v133, 0xbfb8aa3b, v133
	v_mul_f32_e32 v130, 0xbfb8aa3b, v130
	v_mul_f32_e32 v131, 0xbfb8aa3b, v131
	v_exp_f32_e32 v139, v144
	v_exp_f32_e32 v140, v145
	v_exp_f32_e32 v142, v136
	v_exp_f32_e32 v136, v132
	v_exp_f32_e32 v141, v133
	v_exp_f32_e32 v143, v130
	v_exp_f32_e32 v144, v131
	v_add_f32_e32 v130, 1.0, v137
	v_add_f32_e32 v131, 1.0, v138
	v_add_f32_e32 v132, 1.0, v139
	v_add_f32_e32 v133, 1.0, v140
	v_rcp_f32_e32 v130, v130
	v_rcp_f32_e32 v131, v131
	v_add_f32_e32 v136, 1.0, v136
	v_add_f32_e32 v137, 1.0, v141
	v_add_f32_e32 v138, 1.0, v143
	v_add_f32_e32 v139, 1.0, v144
	v_rcp_f32_e32 v132, v132
	v_rcp_f32_e32 v133, v133
	v_rcp_f32_e32 v136, v136
	v_rcp_f32_e32 v137, v137
	v_rcp_f32_e32 v138, v138
	v_rcp_f32_e32 v139, v139
	v_and_b32_e32 v183, 0xffff0000, v174
	v_lshlrev_b32_e32 v180, 16, v172
	v_and_b32_e32 v181, 0xffff0000, v172
	v_lshlrev_b32_e32 v172, 16, v173
	v_and_b32_e32 v173, 0xffff0000, v173
	v_lshlrev_b32_e32 v174, 16, v175
	v_and_b32_e32 v175, 0xffff0000, v175
	v_pk_mul_f32 v[130:131], v[130:131], v[182:183]
	v_pk_fma_f32 v[134:135], v[134:135], v[166:167], v[46:47] op_sel_hi:[1,0,1]
	v_pk_mul_f32 v[140:141], v[132:133], v[174:175]
	v_cvt_pk_bf16_f32 v132, v130, v131
	v_pk_mul_f32 v[130:131], v[136:137], v[180:181]
	v_pk_mul_f32 v[136:137], v[138:139], v[172:173]
	v_mul_f32_e32 v134, 0xbfb8aa3b, v134
	v_mul_f32_e32 v135, 0xbfb8aa3b, v135
	v_cvt_pk_bf16_f32 v133, v140, v141
	v_cvt_pk_bf16_f32 v130, v130, v131
	v_cvt_pk_bf16_f32 v131, v136, v137
	v_exp_f32_e32 v134, v134
	v_exp_f32_e32 v135, v135
	global_store_dwordx4 v[164:165], v[130:133], off
	v_mul_f32_e32 v136, 0xbfb8aa3b, v189
	v_add_f32_e32 v134, 1.0, v134
	v_exp_f32_e32 v131, v163
	v_add_f32_e32 v135, 1.0, v135
	v_rcp_f32_e32 v134, v134
	v_rcp_f32_e32 v135, v135
	v_add_f32_e32 v131, 1.0, v131
	v_rcp_f32_e32 v133, v131
	v_mul_f32_e32 v131, 0xbfb8aa3b, v188
	v_add_f32_e32 v132, 1.0, v142
	v_exp_f32_e32 v131, v131
	v_rcp_f32_e32 v132, v132
	v_exp_f32_e32 v136, v136
	v_lshlrev_b32_e32 v184, 16, v176
	v_and_b32_e32 v185, 0xffff0000, v176
	v_pk_mul_f32 v[134:135], v[134:135], v[184:185]
	v_add_f32_e32 v131, 1.0, v131
	v_cvt_pk_bf16_f32 v130, v134, v135
	v_lshlrev_b32_e32 v134, 16, v177
	v_and_b32_e32 v135, 0xffff0000, v177
	v_pk_mul_f32 v[132:133], v[132:133], v[134:135]
	v_rcp_f32_e32 v134, v131
	v_add_f32_e32 v131, 1.0, v136
	v_rcp_f32_e32 v135, v131
	v_cvt_pk_bf16_f32 v131, v132, v133
	v_lshlrev_b32_e32 v132, 16, v178
	v_and_b32_e32 v133, 0xffff0000, v178
	v_pk_mul_f32 v[132:133], v[134:135], v[132:133]
	v_mul_f32_e32 v134, 0xbfb8aa3b, v186
	v_exp_f32_e32 v134, v134
	v_mul_f32_e32 v135, 0xbfb8aa3b, v187
	v_exp_f32_e32 v135, v135
	v_cvt_pk_bf16_f32 v132, v132, v133
	v_add_f32_e32 v133, 1.0, v134
	v_rcp_f32_e32 v138, v133
	v_add_f32_e32 v133, 1.0, v135
	v_rcp_f32_e32 v139, v133
	v_or_b32_e32 v166, 16, v162
	v_lshlrev_b32_e32 v140, 16, v179
	v_and_b32_e32 v141, 0xffff0000, v179
	v_ashrrev_i32_e32 v167, 31, v166
	v_lshlrev_b64 v[142:143], 11, v[166:167]
	v_pk_mul_f32 v[138:139], v[138:139], v[140:141]
	v_lshl_add_u64 v[134:135], s[8:9], 0, v[142:143]
	v_cvt_pk_bf16_f32 v133, v138, v139
	v_lshl_add_u64 v[144:145], v[134:135], 0, v[160:161]
	global_store_dwordx4 v[164:165], v[130:133], off offset:256
	s_waitcnt vmcnt(14)
	v_mov_b32_e32 v134, v190
	v_mov_b32_e32 v135, v191
	v_mov_b32_e32 v136, v192
	v_mov_b32_e32 v137, v193
	v_lshlrev_b32_e32 v138, 16, v134
	v_lshl_add_u64 v[130:131], v[166:167], 2, s[4:5]
	v_mov_b32_e32 v141, v240
	s_nop 0
	v_mov_b32_e32 v130, v194
	v_mov_b32_e32 v131, v195
	v_mov_b32_e32 v132, v196
	v_mov_b32_e32 v133, v197
	v_and_b32_e32 v139, 0xffff0000, v134
	v_lshlrev_b32_e32 v134, 16, v135
	v_and_b32_e32 v135, 0xffff0000, v135
	v_lshlrev_b32_e32 v140, 16, v136
	v_fmamk_f32 v141, v141, 0x3a800000, v225
	v_rsq_f32_e32 v144, v141
	v_and_b32_e32 v141, 0xffff0000, v136
	v_lshlrev_b32_e32 v136, 16, v137
	v_and_b32_e32 v137, 0xffff0000, v137
	v_pk_fma_f32 v[128:129], v[128:129], v[144:145], v[56:57] op_sel_hi:[1,0,1]
	v_pk_fma_f32 v[126:127], v[126:127], v[144:145], v[54:55] op_sel_hi:[1,0,1]
	v_pk_fma_f32 v[122:123], v[122:123], v[144:145], v[50:51] op_sel_hi:[1,0,1]
	v_pk_fma_f32 v[124:125], v[124:125], v[144:145], v[52:53] op_sel_hi:[1,0,1]
	v_mul_f32_e32 v126, 0xbfb8aa3b, v126
	v_mul_f32_e32 v127, 0xbfb8aa3b, v127
	v_mul_f32_e32 v128, 0xbfb8aa3b, v128
	v_mul_f32_e32 v129, 0xbfb8aa3b, v129
	v_mul_f32_e32 v122, 0xbfb8aa3b, v122
	v_mul_f32_e32 v123, 0xbfb8aa3b, v123
	v_mul_f32_e32 v124, 0xbfb8aa3b, v124
	v_mul_f32_e32 v125, 0xbfb8aa3b, v125
	v_exp_f32_e32 v126, v126
	v_exp_f32_e32 v127, v127
	v_exp_f32_e32 v128, v128
	v_exp_f32_e32 v129, v129
	v_exp_f32_e32 v122, v122
	v_exp_f32_e32 v123, v123
	v_exp_f32_e32 v124, v124
	v_exp_f32_e32 v125, v125
	v_add_f32_e32 v126, 1.0, v126
	v_add_f32_e32 v127, 1.0, v127
	v_add_f32_e32 v128, 1.0, v128
	v_add_f32_e32 v129, 1.0, v129
	v_add_f32_e32 v145, 1.0, v122
	v_add_f32_e32 v163, 1.0, v123
	v_add_f32_e32 v164, 1.0, v124
	v_add_f32_e32 v165, 1.0, v125
	v_rcp_f32_e32 v122, v126
	v_rcp_f32_e32 v123, v127
	v_rcp_f32_e32 v124, v128
	v_rcp_f32_e32 v125, v129
	v_rcp_f32_e32 v126, v145
	v_rcp_f32_e32 v127, v163
	v_rcp_f32_e32 v128, v164
	v_rcp_f32_e32 v129, v165
	v_pk_mul_f32 v[122:123], v[122:123], v[138:139]
	v_pk_mul_f32 v[124:125], v[124:125], v[134:135]
	v_pk_mul_f32 v[126:127], v[126:127], v[140:141]
	v_pk_mul_f32 v[128:129], v[128:129], v[136:137]
	v_cvt_pk_bf16_f32 v122, v122, v123
	v_cvt_pk_bf16_f32 v123, v124, v125
	v_cvt_pk_bf16_f32 v124, v126, v127
	v_lshl_add_u64 v[126:127], s[10:11], 0, v[142:143]
	v_pk_fma_f32 v[118:119], v[118:119], v[144:145], v[46:47] op_sel_hi:[1,0,1]
	v_cvt_pk_bf16_f32 v125, v128, v129
	v_lshl_add_u64 v[126:127], v[126:127], 0, v[160:161]
	v_mul_f32_e32 v118, 0xbfb8aa3b, v118
	global_store_dwordx4 v[126:127], v[122:125], off
	v_pk_fma_f32 v[120:121], v[120:121], v[144:145], v[48:49] op_sel_hi:[1,0,1]
	v_pk_fma_f32 v[116:117], v[116:117], v[144:145], v[40:41] op_sel_hi:[1,0,1]
	v_exp_f32_e32 v122, v118
	v_mul_f32_e32 v118, 0xbfb8aa3b, v119
	v_exp_f32_e32 v123, v118
	v_pk_fma_f32 v[118:119], v[114:115], v[144:145], v[38:39] op_sel_hi:[1,0,1]
	v_add_f32_e32 v114, 1.0, v122
	v_rcp_f32_e32 v114, v114
	v_add_f32_e32 v115, 1.0, v123
	v_rcp_f32_e32 v115, v115
	v_mul_f32_e32 v120, 0xbfb8aa3b, v120
	v_mul_f32_e32 v121, 0xbfb8aa3b, v121
	v_exp_f32_e32 v120, v120
	v_exp_f32_e32 v121, v121
	v_lshlrev_b32_e32 v122, 16, v130
	v_and_b32_e32 v123, 0xffff0000, v130
	v_pk_mul_f32 v[114:115], v[114:115], v[122:123]
	v_add_f32_e32 v120, 1.0, v120
	v_cvt_pk_bf16_f32 v114, v114, v115
	v_mul_f32_e32 v115, 0xbfb8aa3b, v118
	v_add_f32_e32 v121, 1.0, v121
	v_exp_f32_e32 v118, v115
	v_mul_f32_e32 v115, 0xbfb8aa3b, v119
	v_rcp_f32_e32 v120, v120
	v_rcp_f32_e32 v121, v121
	v_exp_f32_e32 v119, v115
	v_lshlrev_b32_e32 v122, 16, v131
	v_and_b32_e32 v123, 0xffff0000, v131
	v_mul_f32_e32 v116, 0xbfb8aa3b, v116
	v_pk_mul_f32 v[120:121], v[120:121], v[122:123]
	v_add_f32_e32 v118, 1.0, v118
	v_add_f32_e32 v119, 1.0, v119
	v_exp_f32_e32 v122, v116
	v_mul_f32_e32 v116, 0xbfb8aa3b, v117
	v_rcp_f32_e32 v118, v118
	v_rcp_f32_e32 v119, v119
	v_exp_f32_e32 v123, v116
	v_cvt_pk_bf16_f32 v115, v120, v121
	v_lshlrev_b32_e32 v120, 16, v132
	v_and_b32_e32 v121, 0xffff0000, v132
	v_pk_mul_f32 v[116:117], v[118:119], v[120:121]
	v_add_f32_e32 v118, 1.0, v122
	v_add_f32_e32 v119, 1.0, v123
	v_rcp_f32_e32 v118, v118
	v_rcp_f32_e32 v119, v119
	v_lshlrev_b32_e32 v120, 16, v133
	v_and_b32_e32 v121, 0xffff0000, v133
	v_cvt_pk_bf16_f32 v116, v116, v117
	v_pk_mul_f32 v[118:119], v[118:119], v[120:121]
	s_nop 0
	v_cvt_pk_bf16_f32 v117, v118, v119
	global_store_dwordx4 v[126:127], v[114:117], off offset:256
	s_nop 1
	v_or_b32_e32 v114, 32, v162
	v_ashrrev_i32_e32 v115, 31, v114
	v_lshlrev_b64 v[122:123], 11, v[114:115]
	v_lshl_add_u64 v[118:119], v[114:115], 2, s[4:5]
	v_lshl_add_u64 v[114:115], s[8:9], 0, v[122:123]
	v_lshl_add_u64 v[120:121], v[114:115], 0, v[160:161]
	s_waitcnt vmcnt(13)
	v_mov_b32_e32 v114, v198
	v_mov_b32_e32 v115, v199
	v_mov_b32_e32 v116, v200
	v_mov_b32_e32 v117, v201
	v_mov_b32_e32 v125, v241
	s_nop 0
	v_mov_b32_e32 v118, v202
	v_mov_b32_e32 v119, v203
	v_mov_b32_e32 v120, v204
	v_mov_b32_e32 v121, v205
	v_lshlrev_b32_e32 v124, 16, v114
	v_fmamk_f32 v125, v125, 0x3a800000, v225
	v_rsq_f32_e32 v126, v125
	v_and_b32_e32 v125, 0xffff0000, v114
	v_lshlrev_b32_e32 v114, 16, v115
	v_and_b32_e32 v115, 0xffff0000, v115
	v_pk_fma_f32 v[112:113], v[112:113], v[126:127], v[56:57] op_sel_hi:[1,0,1]
	v_pk_fma_f32 v[110:111], v[110:111], v[126:127], v[54:55] op_sel_hi:[1,0,1]
	v_pk_fma_f32 v[106:107], v[106:107], v[126:127], v[50:51] op_sel_hi:[1,0,1]
	v_mul_f32_e32 v110, 0xbfb8aa3b, v110
	v_mul_f32_e32 v111, 0xbfb8aa3b, v111
	v_mul_f32_e32 v112, 0xbfb8aa3b, v112
	v_mul_f32_e32 v113, 0xbfb8aa3b, v113
	v_pk_fma_f32 v[108:109], v[108:109], v[126:127], v[52:53] op_sel_hi:[1,0,1]
	v_mul_f32_e32 v127, 0xbfb8aa3b, v106
	v_mul_f32_e32 v128, 0xbfb8aa3b, v107
	v_exp_f32_e32 v106, v110
	v_exp_f32_e32 v107, v111
	v_exp_f32_e32 v110, v112
	v_exp_f32_e32 v111, v113
	v_add_f32_e32 v106, 1.0, v106
	v_add_f32_e32 v107, 1.0, v107
	v_add_f32_e32 v110, 1.0, v110
	v_add_f32_e32 v111, 1.0, v111
	v_rcp_f32_e32 v106, v106
	v_rcp_f32_e32 v107, v107
	v_rcp_f32_e32 v110, v110
	v_rcp_f32_e32 v111, v111
	v_exp_f32_e32 v112, v127
	v_exp_f32_e32 v113, v128
	v_pk_mul_f32 v[106:107], v[106:107], v[124:125]
	v_pk_mul_f32 v[110:111], v[110:111], v[114:115]
	v_mul_f32_e32 v108, 0xbfb8aa3b, v108
	v_cvt_pk_bf16_f32 v106, v106, v107
	v_cvt_pk_bf16_f32 v107, v110, v111
	v_add_f32_e32 v110, 1.0, v112
	v_add_f32_e32 v111, 1.0, v113
	v_exp_f32_e32 v114, v108
	v_mul_f32_e32 v108, 0xbfb8aa3b, v109
	v_rcp_f32_e32 v110, v110
	v_rcp_f32_e32 v111, v111
	v_exp_f32_e32 v115, v108
	v_lshlrev_b32_e32 v112, 16, v116
	v_and_b32_e32 v113, 0xffff0000, v116
	v_pk_mul_f32 v[108:109], v[110:111], v[112:113]
	v_add_f32_e32 v110, 1.0, v114
	v_add_f32_e32 v111, 1.0, v115
	v_rcp_f32_e32 v110, v110
	v_rcp_f32_e32 v111, v111
	v_lshlrev_b32_e32 v112, 16, v117
	v_and_b32_e32 v113, 0xffff0000, v117
	v_cvt_pk_bf16_f32 v108, v108, v109
	v_pk_mul_f32 v[110:111], v[110:111], v[112:113]
	v_pk_fma_f32 v[102:103], v[102:103], v[126:127], v[46:47] op_sel_hi:[1,0,1]
	v_cvt_pk_bf16_f32 v109, v110, v111
	v_lshl_add_u64 v[110:111], s[10:11], 0, v[122:123]
	v_lshl_add_u64 v[110:111], v[110:111], 0, v[160:161]
	v_mul_f32_e32 v102, 0xbfb8aa3b, v102
	global_store_dwordx4 v[110:111], v[106:109], off
	v_pk_fma_f32 v[104:105], v[104:105], v[126:127], v[48:49] op_sel_hi:[1,0,1]
	v_pk_fma_f32 v[100:101], v[100:101], v[126:127], v[40:41] op_sel_hi:[1,0,1]
	v_exp_f32_e32 v106, v102
	v_mul_f32_e32 v102, 0xbfb8aa3b, v103
	v_exp_f32_e32 v107, v102
	v_pk_fma_f32 v[102:103], v[98:99], v[126:127], v[38:39] op_sel_hi:[1,0,1]
	v_add_f32_e32 v98, 1.0, v106
	v_rcp_f32_e32 v98, v98
	v_add_f32_e32 v99, 1.0, v107
	v_rcp_f32_e32 v99, v99
	v_mul_f32_e32 v104, 0xbfb8aa3b, v104
	v_mul_f32_e32 v105, 0xbfb8aa3b, v105
	v_exp_f32_e32 v104, v104
	v_exp_f32_e32 v105, v105
	v_lshlrev_b32_e32 v106, 16, v118
	v_and_b32_e32 v107, 0xffff0000, v118
	v_pk_mul_f32 v[98:99], v[98:99], v[106:107]
	v_add_f32_e32 v104, 1.0, v104
	v_cvt_pk_bf16_f32 v98, v98, v99
	v_mul_f32_e32 v99, 0xbfb8aa3b, v102
	v_add_f32_e32 v105, 1.0, v105
	v_exp_f32_e32 v102, v99
	v_mul_f32_e32 v99, 0xbfb8aa3b, v103
	v_rcp_f32_e32 v104, v104
	v_rcp_f32_e32 v105, v105
	v_exp_f32_e32 v103, v99
	v_lshlrev_b32_e32 v106, 16, v119
	v_and_b32_e32 v107, 0xffff0000, v119
	v_mul_f32_e32 v100, 0xbfb8aa3b, v100
	v_pk_mul_f32 v[104:105], v[104:105], v[106:107]
	v_add_f32_e32 v102, 1.0, v102
	v_add_f32_e32 v103, 1.0, v103
	v_exp_f32_e32 v106, v100
	v_mul_f32_e32 v100, 0xbfb8aa3b, v101
	v_rcp_f32_e32 v102, v102
	v_rcp_f32_e32 v103, v103
	v_exp_f32_e32 v107, v100
	v_cvt_pk_bf16_f32 v99, v104, v105
	v_lshlrev_b32_e32 v104, 16, v120
	v_and_b32_e32 v105, 0xffff0000, v120
	v_pk_mul_f32 v[100:101], v[102:103], v[104:105]
	v_add_f32_e32 v102, 1.0, v106
	v_add_f32_e32 v103, 1.0, v107
	v_rcp_f32_e32 v102, v102
	v_rcp_f32_e32 v103, v103
	v_lshlrev_b32_e32 v104, 16, v121
	v_and_b32_e32 v105, 0xffff0000, v121
	v_cvt_pk_bf16_f32 v100, v100, v101
	v_pk_mul_f32 v[102:103], v[102:103], v[104:105]
	s_nop 0
	v_cvt_pk_bf16_f32 v101, v102, v103
	global_store_dwordx4 v[110:111], v[98:101], off offset:256
	s_nop 1
	v_or_b32_e32 v98, 48, v162
	v_ashrrev_i32_e32 v99, 31, v98
	v_lshl_add_u64 v[100:101], v[98:99], 2, s[4:5]
	s_waitcnt vmcnt(12)
	v_mov_b32_e32 v108, v242
	v_lshlrev_b64 v[102:103], 11, v[98:99]
	v_lshl_add_u64 v[98:99], s[8:9], 0, v[102:103]
	v_lshl_add_u64 v[104:105], v[98:99], 0, v[160:161]
	v_mov_b32_e32 v98, v206
	v_mov_b32_e32 v99, v207
	v_mov_b32_e32 v100, v208
	v_mov_b32_e32 v101, v209
	s_nop 0
	v_mov_b32_e32 v104, v210
	v_mov_b32_e32 v105, v211
	v_mov_b32_e32 v106, v212
	v_mov_b32_e32 v107, v213
	v_fmamk_f32 v108, v108, 0x3a800000, v225
	v_rsq_f32_e32 v108, v108
	v_and_b32_e32 v111, 0xffff0000, v98
	v_pk_fma_f32 v[94:95], v[94:95], v[108:109], v[54:55] op_sel_hi:[1,0,1]
	s_nop 0
	v_mul_f32_e32 v94, 0xbfb8aa3b, v94
	v_pk_fma_f32 v[96:97], v[96:97], v[108:109], v[56:57] op_sel_hi:[1,0,1]
	v_pk_fma_f32 v[92:93], v[92:93], v[108:109], v[52:53] op_sel_hi:[1,0,1]
	v_exp_f32_e32 v109, v94
	v_mul_f32_e32 v94, 0xbfb8aa3b, v95
	v_exp_f32_e32 v110, v94
	v_mul_f32_e32 v96, 0xbfb8aa3b, v96
	v_pk_fma_f32 v[94:95], v[90:91], v[108:109], v[50:51] op_sel_hi:[1,0,1]
	v_add_f32_e32 v90, 1.0, v109
	v_add_f32_e32 v91, 1.0, v110
	v_rcp_f32_e32 v90, v90
	v_rcp_f32_e32 v91, v91
	v_mul_f32_e32 v97, 0xbfb8aa3b, v97
	v_exp_f32_e32 v96, v96
	v_exp_f32_e32 v97, v97
	v_lshlrev_b32_e32 v110, 16, v98
	v_pk_mul_f32 v[90:91], v[90:91], v[110:111]
	v_add_f32_e32 v96, 1.0, v96
	v_cvt_pk_bf16_f32 v90, v90, v91
	v_mul_f32_e32 v91, 0xbfb8aa3b, v94
	v_add_f32_e32 v97, 1.0, v97
	v_exp_f32_e32 v94, v91
	v_mul_f32_e32 v91, 0xbfb8aa3b, v95
	v_rcp_f32_e32 v96, v96
	v_rcp_f32_e32 v97, v97
	v_exp_f32_e32 v95, v91
	v_lshlrev_b32_e32 v98, 16, v99
	v_and_b32_e32 v99, 0xffff0000, v99
	v_mul_f32_e32 v92, 0xbfb8aa3b, v92
	v_pk_mul_f32 v[96:97], v[96:97], v[98:99]
	v_add_f32_e32 v94, 1.0, v94
	v_add_f32_e32 v95, 1.0, v95
	v_exp_f32_e32 v98, v92
	v_mul_f32_e32 v92, 0xbfb8aa3b, v93
	v_rcp_f32_e32 v94, v94
	v_rcp_f32_e32 v95, v95
	v_exp_f32_e32 v99, v92
	v_cvt_pk_bf16_f32 v91, v96, v97
	v_lshlrev_b32_e32 v96, 16, v100
	v_and_b32_e32 v97, 0xffff0000, v100
	v_pk_mul_f32 v[92:93], v[94:95], v[96:97]
	v_add_f32_e32 v94, 1.0, v98
	v_add_f32_e32 v95, 1.0, v99
	v_rcp_f32_e32 v94, v94
	v_rcp_f32_e32 v95, v95
	v_lshlrev_b32_e32 v96, 16, v101
	v_and_b32_e32 v97, 0xffff0000, v101
	v_cvt_pk_bf16_f32 v92, v92, v93
	v_pk_mul_f32 v[94:95], v[94:95], v[96:97]
	v_pk_fma_f32 v[86:87], v[86:87], v[108:109], v[46:47] op_sel_hi:[1,0,1]
	v_cvt_pk_bf16_f32 v93, v94, v95
	v_lshl_add_u64 v[94:95], s[10:11], 0, v[102:103]
	v_lshl_add_u64 v[94:95], v[94:95], 0, v[160:161]
	v_mul_f32_e32 v86, 0xbfb8aa3b, v86
	global_store_dwordx4 v[94:95], v[90:93], off
	v_pk_fma_f32 v[88:89], v[88:89], v[108:109], v[48:49] op_sel_hi:[1,0,1]
	v_pk_fma_f32 v[84:85], v[84:85], v[108:109], v[40:41] op_sel_hi:[1,0,1]
	v_exp_f32_e32 v90, v86
	v_mul_f32_e32 v86, 0xbfb8aa3b, v87
	v_exp_f32_e32 v91, v86
	v_pk_fma_f32 v[86:87], v[82:83], v[108:109], v[38:39] op_sel_hi:[1,0,1]
	v_add_f32_e32 v82, 1.0, v90
	v_rcp_f32_e32 v82, v82
	v_add_f32_e32 v83, 1.0, v91
	v_rcp_f32_e32 v83, v83
	v_mul_f32_e32 v88, 0xbfb8aa3b, v88
	v_mul_f32_e32 v89, 0xbfb8aa3b, v89
	v_exp_f32_e32 v88, v88
	v_exp_f32_e32 v89, v89
	v_lshlrev_b32_e32 v90, 16, v104
	v_and_b32_e32 v91, 0xffff0000, v104
	v_pk_mul_f32 v[82:83], v[82:83], v[90:91]
	v_add_f32_e32 v88, 1.0, v88
	v_cvt_pk_bf16_f32 v82, v82, v83
	v_mul_f32_e32 v83, 0xbfb8aa3b, v86
	v_add_f32_e32 v89, 1.0, v89
	v_exp_f32_e32 v86, v83
	v_mul_f32_e32 v83, 0xbfb8aa3b, v87
	v_rcp_f32_e32 v88, v88
	v_rcp_f32_e32 v89, v89
	v_exp_f32_e32 v87, v83
	v_lshlrev_b32_e32 v90, 16, v105
	v_and_b32_e32 v91, 0xffff0000, v105
	v_mul_f32_e32 v84, 0xbfb8aa3b, v84
	v_pk_mul_f32 v[88:89], v[88:89], v[90:91]
	v_add_f32_e32 v86, 1.0, v86
	v_add_f32_e32 v87, 1.0, v87
	v_exp_f32_e32 v90, v84
	v_mul_f32_e32 v84, 0xbfb8aa3b, v85
	v_rcp_f32_e32 v86, v86
	v_rcp_f32_e32 v87, v87
	v_exp_f32_e32 v91, v84
	v_cvt_pk_bf16_f32 v83, v88, v89
	v_lshlrev_b32_e32 v88, 16, v106
	v_and_b32_e32 v89, 0xffff0000, v106
	v_pk_mul_f32 v[84:85], v[86:87], v[88:89]
	v_add_f32_e32 v86, 1.0, v90
	v_add_f32_e32 v87, 1.0, v91
	v_rcp_f32_e32 v86, v86
	v_rcp_f32_e32 v87, v87
	v_lshlrev_b32_e32 v88, 16, v107
	v_and_b32_e32 v89, 0xffff0000, v107
	v_cvt_pk_bf16_f32 v84, v84, v85
	v_pk_mul_f32 v[86:87], v[86:87], v[88:89]
	s_nop 0
	v_cvt_pk_bf16_f32 v85, v86, v87
	global_store_dwordx4 v[94:95], v[82:85], off offset:256
	s_nop 1
	v_add_u32_e32 v82, 0x80, v162
	v_ashrrev_i32_e32 v83, 31, v82
	v_lshl_add_u64 v[84:85], v[82:83], 2, s[4:5]
	s_waitcnt vmcnt(11)
	v_mov_b32_e32 v92, v243
	v_lshlrev_b64 v[90:91], 11, v[82:83]
	v_lshl_add_u64 v[82:83], s[8:9], 0, v[90:91]
	v_lshl_add_u64 v[86:87], v[82:83], 0, v[160:161]
	v_mov_b32_e32 v82, v214
	v_mov_b32_e32 v83, v215
	v_mov_b32_e32 v84, v216
	v_mov_b32_e32 v85, v217
	s_nop 0
	v_mov_b32_e32 v86, v218
	v_mov_b32_e32 v87, v219
	v_mov_b32_e32 v88, v220
	v_mov_b32_e32 v89, v221
	v_fmamk_f32 v92, v92, 0x3a800000, v225
	v_rsq_f32_e32 v92, v92
	v_and_b32_e32 v95, 0xffff0000, v82
	v_pk_fma_f32 v[78:79], v[78:79], v[92:93], v[54:55] op_sel_hi:[1,0,1]
	s_nop 0
	v_mul_f32_e32 v78, 0xbfb8aa3b, v78
	v_pk_fma_f32 v[80:81], v[80:81], v[92:93], v[56:57] op_sel_hi:[1,0,1]
	v_pk_fma_f32 v[76:77], v[76:77], v[92:93], v[52:53] op_sel_hi:[1,0,1]
	v_exp_f32_e32 v93, v78
	v_mul_f32_e32 v78, 0xbfb8aa3b, v79
	v_exp_f32_e32 v94, v78
	v_mul_f32_e32 v80, 0xbfb8aa3b, v80
	v_pk_fma_f32 v[78:79], v[74:75], v[92:93], v[50:51] op_sel_hi:[1,0,1]
	v_add_f32_e32 v74, 1.0, v93
	v_add_f32_e32 v75, 1.0, v94
	v_rcp_f32_e32 v74, v74
	v_rcp_f32_e32 v75, v75
	v_mul_f32_e32 v81, 0xbfb8aa3b, v81
	v_exp_f32_e32 v80, v80
	v_exp_f32_e32 v81, v81
	v_lshlrev_b32_e32 v94, 16, v82
	v_pk_mul_f32 v[74:75], v[74:75], v[94:95]
	v_add_f32_e32 v80, 1.0, v80
	v_cvt_pk_bf16_f32 v74, v74, v75
	v_mul_f32_e32 v75, 0xbfb8aa3b, v78
	v_add_f32_e32 v81, 1.0, v81
	v_exp_f32_e32 v78, v75
	v_mul_f32_e32 v75, 0xbfb8aa3b, v79
	v_rcp_f32_e32 v80, v80
	v_rcp_f32_e32 v81, v81
	v_exp_f32_e32 v79, v75
	v_lshlrev_b32_e32 v82, 16, v83
	v_and_b32_e32 v83, 0xffff0000, v83
	v_mul_f32_e32 v76, 0xbfb8aa3b, v76
	v_pk_mul_f32 v[80:81], v[80:81], v[82:83]
	v_add_f32_e32 v78, 1.0, v78
	v_add_f32_e32 v79, 1.0, v79
	v_exp_f32_e32 v82, v76
	v_mul_f32_e32 v76, 0xbfb8aa3b, v77
	v_rcp_f32_e32 v78, v78
	v_rcp_f32_e32 v79, v79
	v_exp_f32_e32 v83, v76
	v_cvt_pk_bf16_f32 v75, v80, v81
	v_lshlrev_b32_e32 v80, 16, v84
	v_and_b32_e32 v81, 0xffff0000, v84
	v_pk_mul_f32 v[76:77], v[78:79], v[80:81]
	v_add_f32_e32 v78, 1.0, v82
	v_add_f32_e32 v79, 1.0, v83
	v_rcp_f32_e32 v78, v78
	v_rcp_f32_e32 v79, v79
	v_lshlrev_b32_e32 v80, 16, v85
	v_and_b32_e32 v81, 0xffff0000, v85
	v_cvt_pk_bf16_f32 v76, v76, v77
	v_pk_mul_f32 v[78:79], v[78:79], v[80:81]
	v_pk_fma_f32 v[70:71], v[70:71], v[92:93], v[46:47] op_sel_hi:[1,0,1]
	v_cvt_pk_bf16_f32 v77, v78, v79
	v_lshl_add_u64 v[78:79], s[10:11], 0, v[90:91]
	v_lshl_add_u64 v[78:79], v[78:79], 0, v[160:161]
	v_mul_f32_e32 v70, 0xbfb8aa3b, v70
	global_store_dwordx4 v[78:79], v[74:77], off
	v_pk_fma_f32 v[72:73], v[72:73], v[92:93], v[48:49] op_sel_hi:[1,0,1]
	v_pk_fma_f32 v[68:69], v[68:69], v[92:93], v[40:41] op_sel_hi:[1,0,1]
	v_exp_f32_e32 v74, v70
	v_mul_f32_e32 v70, 0xbfb8aa3b, v71
	v_exp_f32_e32 v75, v70
	v_pk_fma_f32 v[70:71], v[66:67], v[92:93], v[38:39] op_sel_hi:[1,0,1]
	v_add_f32_e32 v66, 1.0, v74
	v_rcp_f32_e32 v66, v66
	v_add_f32_e32 v67, 1.0, v75
	v_rcp_f32_e32 v67, v67
	v_mul_f32_e32 v72, 0xbfb8aa3b, v72
	v_mul_f32_e32 v73, 0xbfb8aa3b, v73
	v_exp_f32_e32 v72, v72
	v_exp_f32_e32 v73, v73
	v_lshlrev_b32_e32 v74, 16, v86
	v_and_b32_e32 v75, 0xffff0000, v86
	v_pk_mul_f32 v[66:67], v[66:67], v[74:75]
	v_add_f32_e32 v72, 1.0, v72
	v_cvt_pk_bf16_f32 v66, v66, v67
	v_mul_f32_e32 v67, 0xbfb8aa3b, v70
	v_add_f32_e32 v73, 1.0, v73
	v_exp_f32_e32 v70, v67
	v_mul_f32_e32 v67, 0xbfb8aa3b, v71
	v_rcp_f32_e32 v72, v72
	v_rcp_f32_e32 v73, v73
	v_exp_f32_e32 v71, v67
	v_lshlrev_b32_e32 v74, 16, v87
	v_and_b32_e32 v75, 0xffff0000, v87
	v_mul_f32_e32 v68, 0xbfb8aa3b, v68
	v_pk_mul_f32 v[72:73], v[72:73], v[74:75]
	v_add_f32_e32 v70, 1.0, v70
	v_add_f32_e32 v71, 1.0, v71
	v_exp_f32_e32 v74, v68
	v_mul_f32_e32 v68, 0xbfb8aa3b, v69
	v_rcp_f32_e32 v70, v70
	v_rcp_f32_e32 v71, v71
	v_exp_f32_e32 v75, v68
	v_cvt_pk_bf16_f32 v67, v72, v73
	v_lshlrev_b32_e32 v72, 16, v88
	v_and_b32_e32 v73, 0xffff0000, v88
	v_pk_mul_f32 v[68:69], v[70:71], v[72:73]
	v_add_f32_e32 v70, 1.0, v74
	v_add_f32_e32 v71, 1.0, v75
	v_rcp_f32_e32 v70, v70
	v_rcp_f32_e32 v71, v71
	v_lshlrev_b32_e32 v72, 16, v89
	v_and_b32_e32 v73, 0xffff0000, v89
	v_cvt_pk_bf16_f32 v68, v68, v69
	v_pk_mul_f32 v[70:71], v[70:71], v[72:73]
	s_nop 0
	v_cvt_pk_bf16_f32 v69, v70, v71
	global_store_dwordx4 v[78:79], v[66:69], off offset:256
	s_nop 1
	v_add_u32_e32 v66, 0x90, v162
	v_ashrrev_i32_e32 v67, 31, v66
	v_lshl_add_u64 v[68:69], v[66:67], 2, s[4:5]
	s_waitcnt vmcnt(10)
	v_mov_b32_e32 v76, v244
	v_lshlrev_b64 v[70:71], 11, v[66:67]
	v_lshl_add_u64 v[66:67], s[8:9], 0, v[70:71]
	v_lshl_add_u64 v[72:73], v[66:67], 0, v[160:161]
	v_mov_b32_e32 v66, v226
	v_mov_b32_e32 v67, v227
	v_mov_b32_e32 v68, v228
	v_mov_b32_e32 v69, v229
	s_nop 0
	v_mov_b32_e32 v72, v236
	v_mov_b32_e32 v73, v237
	v_mov_b32_e32 v74, v238
	v_mov_b32_e32 v75, v239
	v_fmamk_f32 v76, v76, 0x3a800000, v225
	v_rsq_f32_e32 v76, v76
	v_and_b32_e32 v79, 0xffff0000, v66
	v_pk_fma_f32 v[62:63], v[62:63], v[76:77], v[54:55] op_sel_hi:[1,0,1]
	s_nop 0
	v_mul_f32_e32 v62, 0xbfb8aa3b, v62
	v_pk_fma_f32 v[64:65], v[64:65], v[76:77], v[56:57] op_sel_hi:[1,0,1]
	v_pk_fma_f32 v[60:61], v[60:61], v[76:77], v[52:53] op_sel_hi:[1,0,1]
	v_exp_f32_e32 v77, v62
	v_mul_f32_e32 v62, 0xbfb8aa3b, v63
	v_exp_f32_e32 v78, v62
	v_mul_f32_e32 v64, 0xbfb8aa3b, v64
	v_pk_fma_f32 v[62:63], v[58:59], v[76:77], v[50:51] op_sel_hi:[1,0,1]
	v_add_f32_e32 v58, 1.0, v77
	v_add_f32_e32 v59, 1.0, v78
	v_rcp_f32_e32 v58, v58
	v_rcp_f32_e32 v59, v59
	v_mul_f32_e32 v65, 0xbfb8aa3b, v65
	v_exp_f32_e32 v64, v64
	v_exp_f32_e32 v65, v65
	v_lshlrev_b32_e32 v78, 16, v66
	v_pk_mul_f32 v[58:59], v[58:59], v[78:79]
	v_add_f32_e32 v64, 1.0, v64
	v_cvt_pk_bf16_f32 v58, v58, v59
	v_mul_f32_e32 v59, 0xbfb8aa3b, v62
	v_add_f32_e32 v65, 1.0, v65
	v_exp_f32_e32 v62, v59
	v_mul_f32_e32 v59, 0xbfb8aa3b, v63
	v_rcp_f32_e32 v64, v64
	v_rcp_f32_e32 v65, v65
	v_exp_f32_e32 v63, v59
	v_lshlrev_b32_e32 v66, 16, v67
	v_and_b32_e32 v67, 0xffff0000, v67
	v_mul_f32_e32 v60, 0xbfb8aa3b, v60
	v_pk_mul_f32 v[64:65], v[64:65], v[66:67]
	v_add_f32_e32 v62, 1.0, v62
	v_add_f32_e32 v63, 1.0, v63
	v_exp_f32_e32 v66, v60
	v_mul_f32_e32 v60, 0xbfb8aa3b, v61
	v_rcp_f32_e32 v62, v62
	v_rcp_f32_e32 v63, v63
	v_exp_f32_e32 v67, v60
	v_cvt_pk_bf16_f32 v59, v64, v65
	v_lshlrev_b32_e32 v64, 16, v68
	v_and_b32_e32 v65, 0xffff0000, v68
	v_pk_mul_f32 v[60:61], v[62:63], v[64:65]
	v_add_f32_e32 v62, 1.0, v66
	v_add_f32_e32 v63, 1.0, v67
	v_rcp_f32_e32 v62, v62
	v_rcp_f32_e32 v63, v63
	v_lshlrev_b32_e32 v64, 16, v69
	v_and_b32_e32 v65, 0xffff0000, v69
	v_cvt_pk_bf16_f32 v60, v60, v61
	v_pk_mul_f32 v[62:63], v[62:63], v[64:65]
	v_pk_fma_f32 v[42:43], v[42:43], v[76:77], v[46:47] op_sel_hi:[1,0,1]
	v_cvt_pk_bf16_f32 v61, v62, v63
	v_lshl_add_u64 v[62:63], s[10:11], 0, v[70:71]
	v_lshl_add_u64 v[62:63], v[62:63], 0, v[160:161]
	v_mul_f32_e32 v42, 0xbfb8aa3b, v42
	global_store_dwordx4 v[62:63], v[58:61], off
	v_pk_fma_f32 v[44:45], v[44:45], v[76:77], v[48:49] op_sel_hi:[1,0,1]
	v_pk_fma_f32 v[36:37], v[36:37], v[76:77], v[40:41] op_sel_hi:[1,0,1]
	v_exp_f32_e32 v58, v42
	v_mul_f32_e32 v42, 0xbfb8aa3b, v43
	v_exp_f32_e32 v59, v42
	v_pk_fma_f32 v[42:43], v[34:35], v[76:77], v[38:39] op_sel_hi:[1,0,1]
	v_add_f32_e32 v34, 1.0, v58
	v_rcp_f32_e32 v34, v34
	v_add_f32_e32 v35, 1.0, v59
	v_rcp_f32_e32 v35, v35
	v_mul_f32_e32 v44, 0xbfb8aa3b, v44
	v_mul_f32_e32 v45, 0xbfb8aa3b, v45
	v_exp_f32_e32 v44, v44
	v_exp_f32_e32 v45, v45
	v_lshlrev_b32_e32 v58, 16, v72
	v_and_b32_e32 v59, 0xffff0000, v72
	v_pk_mul_f32 v[34:35], v[34:35], v[58:59]
	v_add_f32_e32 v44, 1.0, v44
	v_cvt_pk_bf16_f32 v34, v34, v35
	v_mul_f32_e32 v35, 0xbfb8aa3b, v42
	v_add_f32_e32 v45, 1.0, v45
	v_exp_f32_e32 v42, v35
	v_mul_f32_e32 v35, 0xbfb8aa3b, v43
	v_rcp_f32_e32 v44, v44
	v_rcp_f32_e32 v45, v45
	v_exp_f32_e32 v43, v35
	v_lshlrev_b32_e32 v58, 16, v73
	v_and_b32_e32 v59, 0xffff0000, v73
	v_mul_f32_e32 v36, 0xbfb8aa3b, v36
	v_pk_mul_f32 v[44:45], v[44:45], v[58:59]
	v_add_f32_e32 v42, 1.0, v42
	v_add_f32_e32 v43, 1.0, v43
	v_exp_f32_e32 v58, v36
	v_mul_f32_e32 v36, 0xbfb8aa3b, v37
	v_rcp_f32_e32 v42, v42
	v_rcp_f32_e32 v43, v43
	v_exp_f32_e32 v59, v36
	v_cvt_pk_bf16_f32 v35, v44, v45
	v_lshlrev_b32_e32 v44, 16, v74
	v_and_b32_e32 v45, 0xffff0000, v74
	v_pk_mul_f32 v[36:37], v[42:43], v[44:45]
	v_add_f32_e32 v42, 1.0, v58
	v_add_f32_e32 v43, 1.0, v59
	v_rcp_f32_e32 v42, v42
	v_rcp_f32_e32 v43, v43
	v_lshlrev_b32_e32 v44, 16, v75
	v_and_b32_e32 v45, 0xffff0000, v75
	v_cvt_pk_bf16_f32 v36, v36, v37
	v_pk_mul_f32 v[42:43], v[42:43], v[44:45]
	s_nop 0
	v_cvt_pk_bf16_f32 v37, v42, v43
	global_store_dwordx4 v[62:63], v[34:37], off offset:256
	s_nop 1
	v_add_u32_e32 v34, 0xa0, v162
	v_ashrrev_i32_e32 v35, 31, v34
	v_lshl_add_u64 v[36:37], v[34:35], 2, s[4:5]
	global_load_dword v60, v[36:37], off
	v_lshlrev_b64 v[58:59], 11, v[34:35]
	v_lshl_add_u64 v[34:35], s[8:9], 0, v[58:59]
	v_lshl_add_u64 v[42:43], v[34:35], 0, v[160:161]
	global_load_dwordx4 v[34:37], v[42:43], off
	s_nop 0
	global_load_dwordx4 v[42:45], v[42:43], off offset:256
	s_waitcnt vmcnt(2)
	v_fmamk_f32 v60, v60, 0x3a800000, v225
	v_rsq_f32_e32 v60, v60
	s_waitcnt vmcnt(1)
	v_and_b32_e32 v63, 0xffff0000, v34
	v_pk_fma_f32 v[30:31], v[30:31], v[60:61], v[54:55] op_sel_hi:[1,0,1]
	s_nop 0
	v_mul_f32_e32 v30, 0xbfb8aa3b, v30
	v_pk_fma_f32 v[32:33], v[32:33], v[60:61], v[56:57] op_sel_hi:[1,0,1]
	v_pk_fma_f32 v[28:29], v[28:29], v[60:61], v[52:53] op_sel_hi:[1,0,1]
	v_exp_f32_e32 v61, v30
	v_mul_f32_e32 v30, 0xbfb8aa3b, v31
	v_exp_f32_e32 v62, v30
	v_mul_f32_e32 v32, 0xbfb8aa3b, v32
	v_pk_fma_f32 v[30:31], v[26:27], v[60:61], v[50:51] op_sel_hi:[1,0,1]
	v_add_f32_e32 v26, 1.0, v61
	v_add_f32_e32 v27, 1.0, v62
	v_rcp_f32_e32 v26, v26
	v_rcp_f32_e32 v27, v27
	v_mul_f32_e32 v33, 0xbfb8aa3b, v33
	v_exp_f32_e32 v32, v32
	v_exp_f32_e32 v33, v33
	v_lshlrev_b32_e32 v62, 16, v34
	v_pk_mul_f32 v[26:27], v[26:27], v[62:63]
	v_add_f32_e32 v32, 1.0, v32
	v_cvt_pk_bf16_f32 v26, v26, v27
	v_mul_f32_e32 v27, 0xbfb8aa3b, v30
	v_add_f32_e32 v33, 1.0, v33
	v_exp_f32_e32 v30, v27
	v_mul_f32_e32 v27, 0xbfb8aa3b, v31
	v_rcp_f32_e32 v32, v32
	v_rcp_f32_e32 v33, v33
	v_exp_f32_e32 v31, v27
	v_lshlrev_b32_e32 v34, 16, v35
	v_and_b32_e32 v35, 0xffff0000, v35
	v_mul_f32_e32 v28, 0xbfb8aa3b, v28
	v_pk_mul_f32 v[32:33], v[32:33], v[34:35]
	v_add_f32_e32 v30, 1.0, v30
	v_add_f32_e32 v31, 1.0, v31
	v_exp_f32_e32 v34, v28
	v_mul_f32_e32 v28, 0xbfb8aa3b, v29
	v_rcp_f32_e32 v30, v30
	v_rcp_f32_e32 v31, v31
	v_exp_f32_e32 v35, v28
	v_cvt_pk_bf16_f32 v27, v32, v33
	v_lshlrev_b32_e32 v32, 16, v36
	v_and_b32_e32 v33, 0xffff0000, v36
	v_pk_mul_f32 v[28:29], v[30:31], v[32:33]
	v_add_f32_e32 v30, 1.0, v34
	v_add_f32_e32 v31, 1.0, v35
	v_rcp_f32_e32 v30, v30
	v_rcp_f32_e32 v31, v31
	v_lshlrev_b32_e32 v32, 16, v37
	v_and_b32_e32 v33, 0xffff0000, v37
	v_cvt_pk_bf16_f32 v28, v28, v29
	v_pk_mul_f32 v[30:31], v[30:31], v[32:33]
	v_pk_fma_f32 v[22:23], v[22:23], v[60:61], v[46:47] op_sel_hi:[1,0,1]
	v_cvt_pk_bf16_f32 v29, v30, v31
	v_lshl_add_u64 v[30:31], s[10:11], 0, v[58:59]
	v_lshl_add_u64 v[30:31], v[30:31], 0, v[160:161]
	v_mul_f32_e32 v22, 0xbfb8aa3b, v22
	global_store_dwordx4 v[30:31], v[26:29], off
	v_pk_fma_f32 v[24:25], v[24:25], v[60:61], v[48:49] op_sel_hi:[1,0,1]
	v_pk_fma_f32 v[20:21], v[20:21], v[60:61], v[40:41] op_sel_hi:[1,0,1]
	v_exp_f32_e32 v26, v22
	v_mul_f32_e32 v22, 0xbfb8aa3b, v23
	v_exp_f32_e32 v27, v22
	v_pk_fma_f32 v[22:23], v[18:19], v[60:61], v[38:39] op_sel_hi:[1,0,1]
	v_add_f32_e32 v18, 1.0, v26
	v_rcp_f32_e32 v18, v18
	v_add_f32_e32 v19, 1.0, v27
	v_rcp_f32_e32 v19, v19
	v_mul_f32_e32 v24, 0xbfb8aa3b, v24
	v_mul_f32_e32 v25, 0xbfb8aa3b, v25
	v_exp_f32_e32 v24, v24
	v_exp_f32_e32 v25, v25
	s_waitcnt vmcnt(1)
	v_lshlrev_b32_e32 v26, 16, v42
	v_and_b32_e32 v27, 0xffff0000, v42
	v_pk_mul_f32 v[18:19], v[18:19], v[26:27]
	v_add_f32_e32 v24, 1.0, v24
	v_cvt_pk_bf16_f32 v18, v18, v19
	v_mul_f32_e32 v19, 0xbfb8aa3b, v22
	v_add_f32_e32 v25, 1.0, v25
	v_exp_f32_e32 v22, v19
	v_mul_f32_e32 v19, 0xbfb8aa3b, v23
	v_rcp_f32_e32 v24, v24
	v_rcp_f32_e32 v25, v25
	v_exp_f32_e32 v23, v19
	v_lshlrev_b32_e32 v26, 16, v43
	v_and_b32_e32 v27, 0xffff0000, v43
	v_mul_f32_e32 v20, 0xbfb8aa3b, v20
	v_pk_mul_f32 v[24:25], v[24:25], v[26:27]
	v_add_f32_e32 v22, 1.0, v22
	v_add_f32_e32 v23, 1.0, v23
	v_exp_f32_e32 v26, v20
	v_mul_f32_e32 v20, 0xbfb8aa3b, v21
	v_rcp_f32_e32 v22, v22
	v_rcp_f32_e32 v23, v23
	v_exp_f32_e32 v27, v20
	v_cvt_pk_bf16_f32 v19, v24, v25
	v_lshlrev_b32_e32 v24, 16, v44
	v_and_b32_e32 v25, 0xffff0000, v44
	v_pk_mul_f32 v[20:21], v[22:23], v[24:25]
	v_add_f32_e32 v22, 1.0, v26
	v_add_f32_e32 v23, 1.0, v27
	v_rcp_f32_e32 v22, v22
	v_rcp_f32_e32 v23, v23
	v_lshlrev_b32_e32 v24, 16, v45
	v_and_b32_e32 v25, 0xffff0000, v45
	v_cvt_pk_bf16_f32 v20, v20, v21
	v_pk_mul_f32 v[22:23], v[22:23], v[24:25]
	s_nop 0
	v_cvt_pk_bf16_f32 v21, v22, v23
	global_store_dwordx4 v[30:31], v[18:21], off offset:256
	s_nop 1
	v_add_u32_e32 v18, 0xb0, v162
	v_ashrrev_i32_e32 v19, 31, v18
	v_lshl_add_u64 v[20:21], v[18:19], 2, s[4:5]
	global_load_dword v28, v[20:21], off
	v_lshlrev_b64 v[22:23], 11, v[18:19]
	v_lshl_add_u64 v[18:19], s[8:9], 0, v[22:23]
	v_lshl_add_u64 v[24:25], v[18:19], 0, v[160:161]
	global_load_dwordx4 v[18:21], v[24:25], off
	s_nop 0
	global_load_dwordx4 v[24:27], v[24:25], off offset:256
	s_waitcnt vmcnt(2)
	v_fmamk_f32 v28, v28, 0x3a800000, v225
	v_rsq_f32_e32 v28, v28
	s_waitcnt vmcnt(1)
	v_and_b32_e32 v31, 0xffff0000, v18
	v_pk_fma_f32 v[14:15], v[14:15], v[28:29], v[54:55] op_sel_hi:[1,0,1]
	s_nop 0
	v_mul_f32_e32 v14, 0xbfb8aa3b, v14
	v_pk_fma_f32 v[16:17], v[16:17], v[28:29], v[56:57] op_sel_hi:[1,0,1]
	v_pk_fma_f32 v[12:13], v[12:13], v[28:29], v[52:53] op_sel_hi:[1,0,1]
	v_exp_f32_e32 v29, v14
	v_mul_f32_e32 v14, 0xbfb8aa3b, v15
	v_exp_f32_e32 v30, v14
	v_mul_f32_e32 v16, 0xbfb8aa3b, v16
	v_pk_fma_f32 v[14:15], v[10:11], v[28:29], v[50:51] op_sel_hi:[1,0,1]
	v_add_f32_e32 v10, 1.0, v29
	v_add_f32_e32 v11, 1.0, v30
	v_rcp_f32_e32 v10, v10
	v_rcp_f32_e32 v11, v11
	v_mul_f32_e32 v17, 0xbfb8aa3b, v17
	v_exp_f32_e32 v16, v16
	v_exp_f32_e32 v17, v17
	v_lshlrev_b32_e32 v30, 16, v18
	v_pk_mul_f32 v[10:11], v[10:11], v[30:31]
	v_add_f32_e32 v16, 1.0, v16
	v_cvt_pk_bf16_f32 v10, v10, v11
	v_mul_f32_e32 v11, 0xbfb8aa3b, v14
	v_add_f32_e32 v17, 1.0, v17
	v_exp_f32_e32 v14, v11
	v_mul_f32_e32 v11, 0xbfb8aa3b, v15
	v_rcp_f32_e32 v16, v16
	v_rcp_f32_e32 v17, v17
	v_exp_f32_e32 v15, v11
	v_lshlrev_b32_e32 v18, 16, v19
	v_and_b32_e32 v19, 0xffff0000, v19
	v_mul_f32_e32 v12, 0xbfb8aa3b, v12
	v_pk_mul_f32 v[16:17], v[16:17], v[18:19]
	v_add_f32_e32 v14, 1.0, v14
	v_add_f32_e32 v15, 1.0, v15
	v_exp_f32_e32 v18, v12
	v_mul_f32_e32 v12, 0xbfb8aa3b, v13
	v_rcp_f32_e32 v14, v14
	v_rcp_f32_e32 v15, v15
	v_exp_f32_e32 v19, v12
	v_cvt_pk_bf16_f32 v11, v16, v17
	v_lshlrev_b32_e32 v16, 16, v20
	v_and_b32_e32 v17, 0xffff0000, v20
	v_pk_mul_f32 v[12:13], v[14:15], v[16:17]
	v_add_f32_e32 v14, 1.0, v18
	v_add_f32_e32 v15, 1.0, v19
	v_rcp_f32_e32 v14, v14
	v_rcp_f32_e32 v15, v15
	v_lshlrev_b32_e32 v16, 16, v21
	v_and_b32_e32 v17, 0xffff0000, v21
	v_cvt_pk_bf16_f32 v12, v12, v13
	v_pk_mul_f32 v[14:15], v[14:15], v[16:17]
	v_pk_fma_f32 v[6:7], v[6:7], v[28:29], v[46:47] op_sel_hi:[1,0,1]
	v_cvt_pk_bf16_f32 v13, v14, v15
	v_lshl_add_u64 v[14:15], s[10:11], 0, v[22:23]
	v_lshl_add_u64 v[14:15], v[14:15], 0, v[160:161]
	v_mul_f32_e32 v6, 0xbfb8aa3b, v6
	global_store_dwordx4 v[14:15], v[10:13], off
	v_pk_fma_f32 v[8:9], v[8:9], v[28:29], v[48:49] op_sel_hi:[1,0,1]
	v_pk_fma_f32 v[4:5], v[4:5], v[28:29], v[40:41] op_sel_hi:[1,0,1]
	v_exp_f32_e32 v10, v6
	v_mul_f32_e32 v6, 0xbfb8aa3b, v7
	v_exp_f32_e32 v11, v6
	v_pk_fma_f32 v[6:7], v[2:3], v[28:29], v[38:39] op_sel_hi:[1,0,1]
	v_add_f32_e32 v2, 1.0, v10
	v_rcp_f32_e32 v2, v2
	v_add_f32_e32 v3, 1.0, v11
	v_rcp_f32_e32 v3, v3
	v_mul_f32_e32 v8, 0xbfb8aa3b, v8
	v_mul_f32_e32 v9, 0xbfb8aa3b, v9
	v_exp_f32_e32 v8, v8
	v_exp_f32_e32 v9, v9
	s_waitcnt vmcnt(1)
	v_lshlrev_b32_e32 v10, 16, v24
	v_and_b32_e32 v11, 0xffff0000, v24
	v_pk_mul_f32 v[2:3], v[2:3], v[10:11]
	v_add_f32_e32 v8, 1.0, v8
	v_cvt_pk_bf16_f32 v2, v2, v3
	v_mul_f32_e32 v3, 0xbfb8aa3b, v6
	v_add_f32_e32 v9, 1.0, v9
	v_exp_f32_e32 v6, v3
	v_mul_f32_e32 v3, 0xbfb8aa3b, v7
	v_rcp_f32_e32 v8, v8
	v_rcp_f32_e32 v9, v9
	v_exp_f32_e32 v7, v3
	v_lshlrev_b32_e32 v10, 16, v25
	v_and_b32_e32 v11, 0xffff0000, v25
	v_mul_f32_e32 v4, 0xbfb8aa3b, v4
	v_pk_mul_f32 v[8:9], v[8:9], v[10:11]
	v_add_f32_e32 v6, 1.0, v6
	v_add_f32_e32 v7, 1.0, v7
	v_exp_f32_e32 v10, v4
	v_mul_f32_e32 v4, 0xbfb8aa3b, v5
	v_rcp_f32_e32 v6, v6
	v_rcp_f32_e32 v7, v7
	v_exp_f32_e32 v11, v4
	v_cvt_pk_bf16_f32 v3, v8, v9
	v_lshlrev_b32_e32 v8, 16, v26
	v_and_b32_e32 v9, 0xffff0000, v26
	v_pk_mul_f32 v[4:5], v[6:7], v[8:9]
	v_add_f32_e32 v6, 1.0, v10
	v_add_f32_e32 v7, 1.0, v11
	v_rcp_f32_e32 v6, v6
	v_rcp_f32_e32 v7, v7
	v_lshlrev_b32_e32 v8, 16, v27
	v_and_b32_e32 v9, 0xffff0000, v27
	v_cvt_pk_bf16_f32 v4, v4, v5
	v_pk_mul_f32 v[6:7], v[6:7], v[8:9]
	s_nop 0
	v_cvt_pk_bf16_f32 v5, v6, v7
	global_store_dwordx4 v[14:15], v[2:5], off offset:256
	s_cbranch_vccnz .LBB0_794
	s_andn2_b64 vcc, exec, s[0:1]
	s_cbranch_vccnz .LBB0_793
	s_barrier
	s_branch .LBB0_793
